# v27 + loop-head placement pin: 3 attention main loops and 8 GEMM loop bodies aligned to 64 B (s_nop-filled .p2alignl)
# speedup vs baseline: 1.0036x; 1.0024x over previous
; template <class Epi, class Sched, bool ALIGN_EPI = false, bool SP2 = false>
; __device__ __forceinline__ void gemm_phase(PG8_LAS unsigned char* lds, const Gemm g, const Sched& S, const Epi& E) {
;     ...
;         const bool has_next = S.next(ui + 1, nxt);
;         const char* nA = has_next ? (const char*)g.A + (size_t)nxt.pm * tstep : cA; const char* nB = has_next ? (const char*)g.Bt + (size_t)nxt.pn * tstep : cB;
;         for (int t = 0; t < nt; t += 2) {
;             const bool last = (t == nt - 2);
;             const char* a1 = cA + (size_t)(t + 1) * kstep;
;             const char* a2 = last ? nA : cA + (size_t)(t + 2) * kstep; const char* b2 = last ? nB : cB + (size_t)(t + 2) * kstep;
;             const char* a3 = a2 + kstep; const char* b3 = b2 + kstep;
;     ...
; #pragma unroll
;         for (int a = 0; a < 2; ++a)
; #pragma unroll
;             for (int b = 0; b < 2; ++b)
; #pragma unroll
;                 for (int m = 0; m < 4; ++m)
; #pragma unroll
;                     for (int n = 0; n < 2; ++n) acc[a][b][m][n] = (f32x4){0.f, 0.f, 0.f, 0.f};
;         cur = nxt; cA = nA; cB = nB; ++ui;
.LBB0_509:
	s_ashr_i32 s57, s56, 31
	s_lshl_b64 s[58:59], s[56:57], 19
	s_add_u32 s58, s28, s58
	s_addc_u32 s59, s29, s59
	s_and_b64 s[60:61], s[8:9], exec
	s_cselect_b32 s57, s59, s67
	s_cselect_b32 s63, s58, s66
	s_ashr_i32 s55, s54, 31
	s_lshl_b64 s[60:61], s[54:55], 19
	s_add_u32 s60, s33, s60
	s_addc_u32 s61, s70, s61
	s_and_b64 s[68:69], s[8:9], exec
	s_cselect_b32 s55, s61, s11
	s_cselect_b32 s95, s60, s10
	s_add_u32 s96, s10, 0x100
	s_addc_u32 s97, s11, 0
	s_add_u32 s10, s66, 0x40080
	v_mov_b64_e32 v[0:1], 0
	v_mov_b64_e32 v[2:3], 0
	v_mov_b64_e32 v[4:5], 0
	v_mov_b64_e32 v[6:7], 0
	v_mov_b64_e32 v[8:9], 0
	v_mov_b64_e32 v[10:11], 0
	v_mov_b64_e32 v[12:13], 0
	v_mov_b64_e32 v[14:15], 0
	v_mov_b64_e32 v[16:17], 0
	v_mov_b64_e32 v[18:19], 0
	v_mov_b64_e32 v[20:21], 0
	v_mov_b64_e32 v[22:23], 0
	v_mov_b64_e32 v[24:25], 0
	v_mov_b64_e32 v[26:27], 0
	v_mov_b64_e32 v[28:29], 0
	v_mov_b64_e32 v[30:31], 0
	v_mov_b64_e32 v[32:33], 0
	v_mov_b64_e32 v[34:35], 0
	v_mov_b64_e32 v[36:37], 0
	v_mov_b64_e32 v[38:39], 0
	v_mov_b64_e32 v[40:41], 0
	v_mov_b64_e32 v[42:43], 0
	v_mov_b64_e32 v[44:45], 0
	v_mov_b64_e32 v[46:47], 0
	v_mov_b64_e32 v[48:49], 0
	v_mov_b64_e32 v[50:51], 0
	v_mov_b64_e32 v[52:53], 0
	v_mov_b64_e32 v[54:55], 0
	v_mov_b64_e32 v[56:57], 0
	v_mov_b64_e32 v[58:59], 0
	v_mov_b64_e32 v[60:61], 0
	v_mov_b64_e32 v[62:63], 0
	v_mov_b64_e32 v[64:65], 0
	v_mov_b64_e32 v[66:67], 0
	v_mov_b64_e32 v[68:69], 0
	v_mov_b64_e32 v[70:71], 0
	v_mov_b64_e32 v[72:73], 0
	v_mov_b64_e32 v[74:75], 0
	v_mov_b64_e32 v[76:77], 0
	v_mov_b64_e32 v[78:79], 0
	v_mov_b64_e32 v[80:81], 0
	v_mov_b64_e32 v[82:83], 0
	v_mov_b64_e32 v[84:85], 0
	v_mov_b64_e32 v[86:87], 0
	v_mov_b64_e32 v[88:89], 0
	v_mov_b64_e32 v[90:91], 0
	v_mov_b64_e32 v[92:93], 0
	v_mov_b64_e32 v[94:95], 0
	v_mov_b64_e32 v[96:97], 0
	v_mov_b64_e32 v[98:99], 0
	v_mov_b64_e32 v[100:101], 0
	v_mov_b64_e32 v[102:103], 0
	v_mov_b64_e32 v[104:105], 0
	v_mov_b64_e32 v[106:107], 0
	v_mov_b64_e32 v[108:109], 0
	v_mov_b64_e32 v[110:111], 0
	v_mov_b64_e32 v[112:113], 0
	v_mov_b64_e32 v[114:115], 0
	v_mov_b64_e32 v[116:117], 0
	v_mov_b64_e32 v[118:119], 0
	v_mov_b64_e32 v[120:121], 0
	v_mov_b64_e32 v[122:123], 0
	v_mov_b64_e32 v[124:125], 0
	v_mov_b64_e32 v[126:127], 0
	s_addc_u32 s11, s67, 0
	s_mov_b32 vcc_lo, -2
	.p2alignl 6, 3212836864

; #define WAIT_BAR(N) asm volatile("s_waitcnt vmcnt(" #N ") lgkmcnt(0)\n\ts_barrier":::"memory")
;   #define DMA_K(t,slot) glds16s(Kb+(long)(t)*KVBLK*kp,ksrc,(unsigned)__builtin_amdgcn_readfirstlane(kdst+(slot)))
;   #define DMA_V(t,slot) do{ glds16s(Vb+(long)(t)*KVBLK*vp,vsrc,(unsigned)__builtin_amdgcn_readfirstlane(vdst+(slot))); \
;       if(VH==2) glds16s(Vb+(long)(t)*KVBLK*vp+64,vsrc,(unsigned)__builtin_amdgcn_readfirstlane(vdst+(slot)+8192)); }while(0)
;   #define BIASADD(P0,P1,t) do{ if(HAS_BIAS&&(t)>=tn0&&(t)<tn1){ const lds_f32*bp_=btab+(64*(t)+lanebias); \
;     _Pragma("unroll") for(int r=0;r<16;++r){ P0[r]+=bp_[(r&3)+8*(r>>2)]; P1[r]+=bp_[(r&3)+8*(r>>2)+32]; } } }while(0)
;   #define ROT() do{sv_prev=sv_cur;sv_cur=sv_next;sv_next=(sv_next==2*VSL)?0:sv_next+VSL;}while(0)
;   #define KPRE(tn) do{ const lds_cptr kn_=kp0+(((tn)&3)*KSL); kf[0]=KLD(kn_); kf[1]=KLD(kn_+512); kf[2]=KLD(kn_+2048); kf[3]=KLD(kn_+2560); }while(0)
; template<int VH,bool HAS_BIAS,int MODE> __device__ __forceinline__ void attn_unit2(const bf16*Qb,int qp,const bf16*__restrict__ Kb,int kp,const bf16*__restrict__ Vb,int vp,bf16*Ob,int op,int q0,int NT,const float*relb,char*shm,float lam,const float*subg,float gmul){
;     ...
;   DMA_K(0,0);DMA_V(0,0);DMA_K(1,KSL);
;   bf16x8 qr[4];
;   #pragma unroll
;   for(int d0=0;d0<4;++d0)qr[d0]=*reinterpret_cast<const bf16x8*>(&Qw[(long)r32*qp+d0*16+hi*8]);
;   DMA_K(2,2*KSL);
;   float l_reg=0.f;f32x16 o[2*VH];
;   #pragma unroll
;   for(int d_=0;d_<2*VH;++d_)o[d_]=f32x16{};
;   const f32x16 zero16=f32x16{};
;   f32x16 pA0,pA1,pB0,pB1; bf16x8 kf[4];
;   int sv_prev=0,sv_cur=0,sv_next=VSL;
;     ...
;   if(VH==1){WAIT_BAR(3);}else{WAIT_BAR(4);}
;   qkt(pA0,pA1,shm+LM::L_K,qr,zero16,r32,hi);
;   BIASADD(pA0,pA1,0);
;   _Pragma("unroll") for(int r=0;r<16;++r){pA0[r]=__builtin_amdgcn_exp2f(pA0[r]);pA1[r]=__builtin_amdgcn_exp2f(pA1[r]);}
;   WAIT_BAR(0);
;   DMA_K(3,3*KSL);DMA_V(1,VSL);
;   ROT();
;   KPRE(1);
.LBB0_614:
	s_lshl_b64 s[10:11], s[6:7], 10
	s_lshl_b64 s[8:9], s[6:7], 11
	s_add_u32 s4, s38, s8
	s_addc_u32 s14, s39, s9
	s_lshl_b32 s8, s13, 6
	s_ashr_i32 s9, s8, 31
	s_lshl_b64 s[8:9], s[8:9], 1
	s_add_u32 s15, s4, s8
	s_addc_u32 s14, s14, s9
	s_lshl_b64 s[6:7], s[6:7], 9
	s_add_u32 s4, s33, s6
	s_addc_u32 s13, s46, s7
	s_lshl_b32 s20, s12, 7
	s_add_u32 s12, s4, s20
	s_addc_u32 s13, s13, 0
	s_add_u32 s4, s47, s6
	s_addc_u32 s6, s48, s7
	v_mov_b32_e32 v44, v182
	s_add_u32 s20, s4, s20
	s_addc_u32 s21, s6, 0
	v_readfirstlane_b32 s52, v44
	s_ashr_i32 s4, s52, 6
	s_lshl_b32 s6, s22, 8
	s_lshl_b32 s7, s4, 5
	s_add_i32 s6, s7, s6
	s_ashr_i32 s7, s6, 31
	s_lshl_b64 s[6:7], s[6:7], 11
	s_add_u32 s22, s15, s6
	v_and_b32_e32 v158, 63, v44
	s_addc_u32 s23, s14, s7
	s_lshl_b32 s14, s4, 4
	v_bfe_u32 v0, v44, 2, 4
	v_lshl_add_u32 v169, v158, 9, s14
	v_and_or_b32 v0, s14, 48, v0
	s_ashr_i32 s14, s52, 3
	s_and_b32 s14, s14, 0x7fffffe0
	s_lshl_b32 s54, s4, 10
	s_cmp_lg_u32 0, -1
	v_lshl_add_u32 v0, v0, 8, s14
	v_lshlrev_b32_e32 v160, 3, v44
	s_cselect_b32 s14, 0, 0
	v_and_b32_e32 v165, 24, v160
	s_add_i32 s54, s54, s14
	v_and_b32_e32 v161, 31, v44
	v_or_b32_e32 v0, v0, v165
	s_add_i32 s55, s54, 0x8000
	s_mov_b32 m0, s54
	s_nop 0
	global_load_lds_dwordx4 v169, s[12:13]
	v_bfe_u32 v162, v44, 5, 1
	v_lshlrev_b32_e32 v170, 1, v0
	s_mov_b32 m0, s55
	s_nop 0
	global_load_lds_dwordx4 v170, s[20:21]
	s_add_u32 s34, s12, 0x8000
	v_lshlrev_b32_e32 v0, 11, v161
	s_addc_u32 s35, s13, 0
	s_add_i32 s14, s54, 0x2000
	s_mov_b32 m0, s14
	s_nop 0
	global_load_lds_dwordx4 v169, s[34:35]
	v_lshl_or_b32 v0, v162, 4, v0
	global_load_dwordx4 v[124:127], v0, s[22:23]
	global_load_dwordx4 v[120:123], v0, s[22:23] offset:32
	global_load_dwordx4 v[116:119], v0, s[22:23] offset:64
	global_load_dwordx4 v[112:115], v0, s[22:23] offset:96
	s_add_u32 s22, s12, 0x10000
	v_lshlrev_b32_e32 v0, 10, v162
	v_lshlrev_b32_e32 v1, 4, v161
	s_addc_u32 s23, s13, 0
	s_add_i32 s14, s54, 0x4000
	s_mov_b32 m0, s14
	s_nop 0
	global_load_lds_dwordx4 v169, s[22:23]
	v_add3_u32 v164, 0, v0, v1
	s_waitcnt vmcnt(3) lgkmcnt(0)
	s_barrier
	ds_read_b128 v[0:3], v164
	ds_read_b128 v[16:19], v164 offset:512
	ds_read_b128 v[32:35], v164 offset:2048
	s_add_u32 s22, s12, 0x18000
	s_addc_u32 s23, s13, 0
	s_add_i32 s14, s54, 0x6000
	s_add_u32 s34, s20, 0x8000
	s_addc_u32 s35, s21, 0
	s_add_i32 s61, s53, -5
	v_mov_b32_e32 v168, 0
	s_mov_b32 s57, 1
	s_mov_b32 s65, 5
	s_mov_b32 s64, 0
	s_mov_b32 s66, 0x8000
	s_movk_i32 s56, 0x2000
	s_mov_b64 s[44:45], 0x10000
	s_movk_i32 s63, 0x4000
	s_movk_i32 s60, 0x4000
	s_waitcnt vmcnt(3) lgkmcnt(2)
	v_mfma_f32_32x32x16_bf16 v[0:15], v[0:3], v[124:127], 0
	s_waitcnt vmcnt(2) lgkmcnt(0)
	v_mfma_f32_32x32x16_bf16 v[0:15], v[32:35], v[120:123], v[0:15]
	ds_read_b128 v[32:35], v164 offset:2560
	ds_read_b128 v[36:39], v164 offset:4608
	ds_read_b128 v[40:43], v164 offset:4096
	v_mfma_f32_32x32x16_bf16 v[16:31], v[16:19], v[124:127], 0
	s_waitcnt lgkmcnt(2)
	v_mfma_f32_32x32x16_bf16 v[16:31], v[32:35], v[120:123], v[16:31]
	v_lshlrev_b32_e32 v32, 1, v44
	v_lshlrev_b32_e32 v33, 4, v44
	v_and_b32_e32 v166, 32, v32
	v_and_b32_e32 v32, 0xc0, v33
	v_lshl_or_b32 v163, v162, 8, v32
	v_add_u32_e32 v32, 0, v166
	v_add3_u32 v167, v32, v165, v163
	s_waitcnt vmcnt(1) lgkmcnt(0)
	v_mfma_f32_32x32x16_bf16 v[0:15], v[40:43], v[116:119], v[0:15]
	ds_read_b128 v[32:35], v164 offset:6656
	ds_read_b128 v[40:43], v164 offset:6144
	s_waitcnt vmcnt(0) lgkmcnt(0)
	s_barrier
	s_mov_b32 m0, s14
	s_nop 0
	global_load_lds_dwordx4 v169, s[22:23]
	s_add_i32 s14, s54, 0xa000
	s_mov_b32 m0, s14
	s_nop 0
	global_load_lds_dwordx4 v170, s[34:35]
	ds_read_b128 v[128:131], v164 offset:10752
	ds_read_b128 v[132:135], v164 offset:10240
	ds_read_b128 v[136:139], v164 offset:8704
	ds_read_b128 v[80:83], v164 offset:8192
	s_add_u32 s40, s20, 0x18000
	v_mfma_f32_32x32x16_bf16 v[16:31], v[36:39], v[116:119], v[16:31]
	s_addc_u32 s41, s21, 0
	s_add_u32 s42, s12, 0x28000
	s_addc_u32 s43, s13, 0
	s_waitcnt lgkmcnt(4)
	v_mfma_f32_32x32x16_bf16 v[0:15], v[40:43], v[112:115], v[0:15]
	v_mfma_f32_32x32x16_bf16 v[16:31], v[32:35], v[112:115], v[16:31]
	s_nop 10
	v_exp_f32_e32 v48, v0
	v_exp_f32_e32 v49, v1
	v_exp_f32_e32 v50, v2
	v_exp_f32_e32 v51, v3
	v_exp_f32_e32 v52, v4
	v_exp_f32_e32 v53, v5
	v_exp_f32_e32 v54, v6
	v_exp_f32_e32 v32, v16
	v_exp_f32_e32 v33, v17
	v_exp_f32_e32 v34, v18
	v_exp_f32_e32 v35, v19
	v_exp_f32_e32 v36, v20
	v_exp_f32_e32 v37, v21
	v_exp_f32_e32 v38, v22
	v_exp_f32_e32 v39, v23
	v_exp_f32_e32 v40, v24
	v_exp_f32_e32 v41, v25
	v_exp_f32_e32 v42, v26
	v_exp_f32_e32 v43, v27
	v_exp_f32_e32 v44, v28
	v_exp_f32_e32 v45, v29
	v_exp_f32_e32 v46, v30
	v_exp_f32_e32 v47, v31
	v_exp_f32_e32 v55, v7
	v_exp_f32_e32 v56, v8
	v_exp_f32_e32 v57, v9
	v_exp_f32_e32 v58, v10
	v_exp_f32_e32 v59, v11
	v_exp_f32_e32 v60, v12
	v_exp_f32_e32 v61, v13
	v_exp_f32_e32 v62, v14
	v_exp_f32_e32 v63, v15
	v_mov_b32_e32 v0, 0
	v_mov_b32_e32 v1, v168
	v_mov_b32_e32 v2, v168
	v_mov_b32_e32 v3, v168
	v_mov_b32_e32 v4, v168
	v_mov_b32_e32 v5, v168
	v_mov_b32_e32 v6, v168
	v_mov_b32_e32 v7, v168
	v_mov_b32_e32 v8, v168
	v_mov_b32_e32 v9, v168
	v_mov_b32_e32 v10, v168
	v_mov_b32_e32 v11, v168
	v_mov_b32_e32 v12, v168
	v_mov_b32_e32 v13, v168
	v_mov_b32_e32 v14, v168
	v_mov_b32_e32 v15, v168
	v_mov_b32_e32 v16, 0
	v_mov_b32_e32 v17, v168
	v_mov_b32_e32 v18, v168
	v_mov_b32_e32 v19, v168
	v_mov_b32_e32 v20, v168
	v_mov_b32_e32 v21, v168
	v_mov_b32_e32 v22, v168
	v_mov_b32_e32 v23, v168
	v_mov_b32_e32 v24, v168
	v_mov_b32_e32 v25, v168
	v_mov_b32_e32 v26, v168
	v_mov_b32_e32 v27, v168
	v_mov_b32_e32 v28, v168
	v_mov_b32_e32 v29, v168
	v_mov_b32_e32 v30, v168
	v_mov_b32_e32 v31, v168
	.p2alignl 6, 3212836864

; template <class Epi, class Sched, bool ALIGN_EPI = false, bool SP2 = false>
; __device__ __forceinline__ void gemm_phase(PG8_LAS unsigned char* lds, const Gemm g, const Sched& S, const Epi& E) {
;     ...
;         const bool has_next = S.next(ui + 1, nxt);
;         const char* nA = has_next ? (const char*)g.A + (size_t)nxt.pm * tstep : cA; const char* nB = has_next ? (const char*)g.Bt + (size_t)nxt.pn * tstep : cB;
;         for (int t = 0; t < nt; t += 2) {
;             const bool last = (t == nt - 2);
;             const char* a1 = cA + (size_t)(t + 1) * kstep;
;             const char* a2 = last ? nA : cA + (size_t)(t + 2) * kstep; const char* b2 = last ? nB : cB + (size_t)(t + 2) * kstep;
;             const char* a3 = a2 + kstep; const char* b3 = b2 + kstep;
;     ...
; #pragma unroll
;         for (int a = 0; a < 2; ++a)
; #pragma unroll
;             for (int b = 0; b < 2; ++b)
; #pragma unroll
;                 for (int m = 0; m < 4; ++m)
; #pragma unroll
;                     for (int n = 0; n < 2; ++n) acc[a][b][m][n] = (f32x4){0.f, 0.f, 0.f, 0.f};
;         cur = nxt; cA = nA; cB = nB; ++ui;
.LBB0_709:
	s_ashr_i32 s45, s44, 31
	s_lshl_b64 s[34:35], s[44:45], 19
	s_add_u32 s46, s33, s34
	s_addc_u32 s47, s60, s35
	s_and_b64 s[34:35], s[8:9], exec
	s_cselect_b32 s45, s47, s57
	s_cselect_b32 s51, s46, s56
	s_ashr_i32 s43, s42, 31
	s_lshl_b64 s[34:35], s[42:43], 19
	s_add_u32 s48, s61, s34
	s_addc_u32 s49, s62, s35
	s_and_b64 s[34:35], s[8:9], exec
	s_cselect_b32 s43, s49, s55
	s_cselect_b32 s53, s48, s54
	s_add_u32 s82, s54, 0x100
	s_addc_u32 s83, s55, 0
	s_add_u32 s54, s56, 0x40080
	v_mov_b64_e32 v[0:1], 0
	v_mov_b64_e32 v[2:3], 0
	v_mov_b64_e32 v[4:5], 0
	v_mov_b64_e32 v[6:7], 0
	v_mov_b64_e32 v[8:9], 0
	v_mov_b64_e32 v[10:11], 0
	v_mov_b64_e32 v[12:13], 0
	v_mov_b64_e32 v[14:15], 0
	v_mov_b64_e32 v[16:17], 0
	v_mov_b64_e32 v[18:19], 0
	v_mov_b64_e32 v[20:21], 0
	v_mov_b64_e32 v[22:23], 0
	v_mov_b64_e32 v[24:25], 0
	v_mov_b64_e32 v[26:27], 0
	v_mov_b64_e32 v[28:29], 0
	v_mov_b64_e32 v[30:31], 0
	v_mov_b64_e32 v[32:33], 0
	v_mov_b64_e32 v[34:35], 0
	v_mov_b64_e32 v[36:37], 0
	v_mov_b64_e32 v[38:39], 0
	v_mov_b64_e32 v[40:41], 0
	v_mov_b64_e32 v[42:43], 0
	v_mov_b64_e32 v[44:45], 0
	v_mov_b64_e32 v[46:47], 0
	v_mov_b64_e32 v[48:49], 0
	v_mov_b64_e32 v[50:51], 0
	v_mov_b64_e32 v[52:53], 0
	v_mov_b64_e32 v[54:55], 0
	v_mov_b64_e32 v[56:57], 0
	v_mov_b64_e32 v[58:59], 0
	v_mov_b64_e32 v[60:61], 0
	v_mov_b64_e32 v[62:63], 0
	v_mov_b64_e32 v[64:65], 0
	v_mov_b64_e32 v[66:67], 0
	v_mov_b64_e32 v[68:69], 0
	v_mov_b64_e32 v[70:71], 0
	v_mov_b64_e32 v[72:73], 0
	v_mov_b64_e32 v[74:75], 0
	v_mov_b64_e32 v[76:77], 0
	v_mov_b64_e32 v[78:79], 0
	v_mov_b64_e32 v[80:81], 0
	v_mov_b64_e32 v[82:83], 0
	v_mov_b64_e32 v[84:85], 0
	v_mov_b64_e32 v[86:87], 0
	v_mov_b64_e32 v[88:89], 0
	v_mov_b64_e32 v[90:91], 0
	v_mov_b64_e32 v[92:93], 0
	v_mov_b64_e32 v[94:95], 0
	v_mov_b64_e32 v[96:97], 0
	v_mov_b64_e32 v[98:99], 0
	v_mov_b64_e32 v[100:101], 0
	v_mov_b64_e32 v[102:103], 0
	v_mov_b64_e32 v[104:105], 0
	v_mov_b64_e32 v[106:107], 0
	v_mov_b64_e32 v[108:109], 0
	v_mov_b64_e32 v[110:111], 0
	v_mov_b64_e32 v[112:113], 0
	v_mov_b64_e32 v[114:115], 0
	v_mov_b64_e32 v[116:117], 0
	v_mov_b64_e32 v[118:119], 0
	v_mov_b64_e32 v[120:121], 0
	v_mov_b64_e32 v[122:123], 0
	v_mov_b64_e32 v[124:125], 0
	v_mov_b64_e32 v[126:127], 0
	s_addc_u32 s55, s57, 0
	s_mov_b32 s84, -2
	s_waitcnt lgkmcnt(0)
	.p2alignl 6, 3212836864

; #define PG8_LAS __attribute__((address_space(3)))
;     __device__ __forceinline__ void prefetch(PG8_LAS unsigned char* sp, const Unit& u, int wid, int lane) const {
;         const int seq = (u.pm < 256) ? (u.pm >> 3) : 32;
;         const float* src = (wid < 4) ? rowss + u.pm * BM + wid * 64 : bias + (size_t)seq * 5632 + u.pn * HALF + (wid < 6 ? (wid - 4) * 64 : 2816 + (wid - 6) * 64);
;         __builtin_amdgcn_global_load_lds((const unsigned*)(src + lane), (PG8_LAS unsigned*)(sp + wid * 256), 4, 0, 0);
; template <class Epi, class Sched, bool ALIGN_EPI = false, bool SP2 = false>
; __device__ __forceinline__ void gemm_phase(PG8_LAS unsigned char* lds, const Gemm g, const Sched& S, const Epi& E) {
;     ...
; #pragma unroll
;         for (int a = 0; a < 2; ++a)
; #pragma unroll
;             for (int b = 0; b < 2; ++b)
; #pragma unroll
;                 for (int m = 0; m < 4; ++m)
; #pragma unroll
;                     for (int n = 0; n < 2; ++n) acc[a][b][m][n] = (f32x4){0.f, 0.f, 0.f, 0.f};
;         cur = nxt; cA = nA; cB = nB; ++ui;
.LBB0_795:
	s_ashr_i32 s43, s42, 31
	s_lshl_b64 s[34:35], s[42:43], 19
	s_add_u32 s44, s28, s34
	s_addc_u32 s45, s29, s35
	s_and_b64 s[34:35], s[6:7], exec
	s_cselect_b32 s43, s45, s57
	s_cselect_b32 s78, s44, s56
	s_ashr_i32 s41, s40, 31
	s_lshl_b64 s[34:35], s[40:41], 19
	s_add_u32 s46, s33, s34
	s_addc_u32 s47, s58, s35
	s_and_b64 s[34:35], s[6:7], exec
	s_cselect_b32 s41, s47, s53
	s_cselect_b32 s79, s46, s52
	s_lshl_b32 s48, s48, 7
	s_lshl_b32 s50, s54, 8
	s_ashr_i32 s12, s54, 3
	s_ashr_i32 s49, s48, 31
	s_ashr_i32 s51, s50, 31
	s_cmpk_lt_i32 s54, 0x100
	s_mul_i32 s13, s12, 0x1600
	s_mul_hi_i32 s12, s12, 0x1600
	s_cselect_b32 s35, s12, 0
	s_cselect_b32 s34, s13, 0x2c000
	s_lshl_b64 s[34:35], s[34:35], 2
	s_add_u32 s12, s66, s34
	s_addc_u32 s13, s67, s35
	s_lshl_b64 s[34:35], s[48:49], 2
	s_add_u32 s12, s12, s34
	s_addc_u32 s13, s13, s35
	s_add_u32 s12, s12, s10
	s_addc_u32 s13, s13, s11
	s_lshl_b64 s[34:35], s[50:51], 2
	s_add_u32 s14, s73, s34
	s_addc_u32 s15, s74, s35
	s_and_b64 s[34:35], s[22:23], exec
	s_cselect_b32 s35, s15, s13
	s_cselect_b32 s34, s14, s12
	s_add_u32 s49, s52, 0x100
	s_addc_u32 s51, s53, 0
	s_add_u32 s52, s56, 0x40080
	v_mov_b64_e32 v[0:1], 0
	v_mov_b64_e32 v[2:3], 0
	v_mov_b64_e32 v[4:5], 0
	v_mov_b64_e32 v[6:7], 0
	v_mov_b64_e32 v[8:9], 0
	v_mov_b64_e32 v[10:11], 0
	v_mov_b64_e32 v[12:13], 0
	v_mov_b64_e32 v[14:15], 0
	v_mov_b64_e32 v[16:17], 0
	v_mov_b64_e32 v[18:19], 0
	v_mov_b64_e32 v[20:21], 0
	v_mov_b64_e32 v[22:23], 0
	v_mov_b64_e32 v[24:25], 0
	v_mov_b64_e32 v[26:27], 0
	v_mov_b64_e32 v[28:29], 0
	v_mov_b64_e32 v[30:31], 0
	v_mov_b64_e32 v[32:33], 0
	v_mov_b64_e32 v[34:35], 0
	v_mov_b64_e32 v[36:37], 0
	v_mov_b64_e32 v[38:39], 0
	v_mov_b64_e32 v[40:41], 0
	v_mov_b64_e32 v[42:43], 0
	v_mov_b64_e32 v[44:45], 0
	v_mov_b64_e32 v[46:47], 0
	v_mov_b64_e32 v[48:49], 0
	v_mov_b64_e32 v[50:51], 0
	v_mov_b64_e32 v[52:53], 0
	v_mov_b64_e32 v[54:55], 0
	v_mov_b64_e32 v[56:57], 0
	v_mov_b64_e32 v[58:59], 0
	v_mov_b64_e32 v[60:61], 0
	v_mov_b64_e32 v[62:63], 0
	v_mov_b64_e32 v[64:65], 0
	v_mov_b64_e32 v[66:67], 0
	v_mov_b64_e32 v[68:69], 0
	v_mov_b64_e32 v[70:71], 0
	v_mov_b64_e32 v[72:73], 0
	v_mov_b64_e32 v[74:75], 0
	v_mov_b64_e32 v[76:77], 0
	v_mov_b64_e32 v[78:79], 0
	v_mov_b64_e32 v[80:81], 0
	v_mov_b64_e32 v[82:83], 0
	v_mov_b64_e32 v[84:85], 0
	v_mov_b64_e32 v[86:87], 0
	v_mov_b64_e32 v[88:89], 0
	v_mov_b64_e32 v[90:91], 0
	v_mov_b64_e32 v[92:93], 0
	v_mov_b64_e32 v[94:95], 0
	v_mov_b64_e32 v[96:97], 0
	v_mov_b64_e32 v[98:99], 0
	v_mov_b64_e32 v[100:101], 0
	v_mov_b64_e32 v[102:103], 0
	v_mov_b64_e32 v[104:105], 0
	v_mov_b64_e32 v[106:107], 0
	v_mov_b64_e32 v[108:109], 0
	v_mov_b64_e32 v[110:111], 0
	v_mov_b64_e32 v[112:113], 0
	v_mov_b64_e32 v[114:115], 0
	v_mov_b64_e32 v[132:133], 0
	v_mov_b64_e32 v[134:135], 0
	v_mov_b64_e32 v[136:137], 0
	v_mov_b64_e32 v[138:139], 0
	v_mov_b64_e32 v[140:141], 0
	v_mov_b64_e32 v[142:143], 0
	v_lshl_add_u64 v[116:117], s[34:35], 0, v[162:163]
	s_addc_u32 s53, s57, 0
	s_mov_b32 s80, -2
	s_branch .LBB0_797
	.p2alignl 6, 3212836864

; template <class Epi, class Sched, bool ALIGN_EPI = false, bool SP2 = false>
; __device__ __forceinline__ void gemm_phase(PG8_LAS unsigned char* lds, const Gemm g, const Sched& S, const Epi& E) {
;     ...
;             const char* a1 = cA + (size_t)(t + 1) * kstep;
;             const char* a2 = last ? nA : cA + (size_t)(t + 2) * kstep; const char* b2 = last ? nB : cB + (size_t)(t + 2) * kstep;
;     ...
; #pragma unroll
;         for (int a = 0; a < 2; ++a)
; #pragma unroll
;             for (int b = 0; b < 2; ++b)
; #pragma unroll
;                 for (int m = 0; m < 4; ++m)
; #pragma unroll
;                     for (int n = 0; n < 2; ++n) acc[a][b][m][n] = (f32x4){0.f, 0.f, 0.f, 0.f};
;         cur = nxt; cA = nA; cB = nB; ++ui;
.LBB0_871:
	s_add_u32 s71, s42, 0x100
	v_mov_b64_e32 v[0:1], 0
	v_mov_b64_e32 v[2:3], 0
	v_mov_b64_e32 v[4:5], 0
	v_mov_b64_e32 v[6:7], 0
	v_mov_b64_e32 v[8:9], 0
	v_mov_b64_e32 v[10:11], 0
	v_mov_b64_e32 v[12:13], 0
	v_mov_b64_e32 v[14:15], 0
	v_mov_b64_e32 v[16:17], 0
	v_mov_b64_e32 v[18:19], 0
	v_mov_b64_e32 v[20:21], 0
	v_mov_b64_e32 v[22:23], 0
	v_mov_b64_e32 v[24:25], 0
	v_mov_b64_e32 v[26:27], 0
	v_mov_b64_e32 v[28:29], 0
	v_mov_b64_e32 v[30:31], 0
	v_mov_b64_e32 v[32:33], 0
	v_mov_b64_e32 v[34:35], 0
	v_mov_b64_e32 v[36:37], 0
	v_mov_b64_e32 v[38:39], 0
	v_mov_b64_e32 v[40:41], 0
	v_mov_b64_e32 v[42:43], 0
	v_mov_b64_e32 v[44:45], 0
	v_mov_b64_e32 v[46:47], 0
	v_mov_b64_e32 v[48:49], 0
	v_mov_b64_e32 v[50:51], 0
	v_mov_b64_e32 v[52:53], 0
	v_mov_b64_e32 v[54:55], 0
	v_mov_b64_e32 v[56:57], 0
	v_mov_b64_e32 v[58:59], 0
	v_mov_b64_e32 v[60:61], 0
	v_mov_b64_e32 v[62:63], 0
	v_mov_b64_e32 v[64:65], 0
	v_mov_b64_e32 v[66:67], 0
	v_mov_b64_e32 v[68:69], 0
	v_mov_b64_e32 v[70:71], 0
	v_mov_b64_e32 v[72:73], 0
	v_mov_b64_e32 v[74:75], 0
	v_mov_b64_e32 v[76:77], 0
	v_mov_b64_e32 v[78:79], 0
	v_mov_b64_e32 v[80:81], 0
	v_mov_b64_e32 v[82:83], 0
	v_mov_b64_e32 v[84:85], 0
	v_mov_b64_e32 v[86:87], 0
	v_mov_b64_e32 v[88:89], 0
	v_mov_b64_e32 v[90:91], 0
	v_mov_b64_e32 v[92:93], 0
	v_mov_b64_e32 v[94:95], 0
	v_mov_b64_e32 v[96:97], 0
	v_mov_b64_e32 v[98:99], 0
	v_mov_b64_e32 v[100:101], 0
	v_mov_b64_e32 v[102:103], 0
	v_mov_b64_e32 v[104:105], 0
	v_mov_b64_e32 v[106:107], 0
	v_mov_b64_e32 v[108:109], 0
	v_mov_b64_e32 v[110:111], 0
	v_mov_b64_e32 v[112:113], 0
	v_mov_b64_e32 v[114:115], 0
	v_mov_b64_e32 v[116:117], 0
	v_mov_b64_e32 v[118:119], 0
	v_mov_b64_e32 v[120:121], 0
	v_mov_b64_e32 v[122:123], 0
	v_mov_b64_e32 v[124:125], 0
	v_mov_b64_e32 v[126:127], 0
	s_addc_u32 s73, s43, 0
	s_mov_b32 s74, -2
	s_waitcnt lgkmcnt(0)
	.p2alignl 6, 3212836864

; #define PG8_LAS __attribute__((address_space(3)))
;     __device__ __forceinline__ void prefetch(PG8_LAS unsigned char* sp, const Unit& u, int wid, int lane) const {
;         if (PRE) { const int seq = (u.pm < 256) ? (u.pm >> 3) : 32;
;             const float* src = (wid < 4) ? rowss + u.pm * BM + wid * 64 : bias + (size_t)seq * N + u.pn * BM + (wid - 4) * 64;
;             __builtin_amdgcn_global_load_lds((const unsigned*)(src + lane), (PG8_LAS unsigned*)(sp + wid * 256), 4, 0, 0); }
;     }
; template <class Epi, class Sched, bool ALIGN_EPI = false, bool SP2 = false>
; __device__ __forceinline__ void gemm_phase(PG8_LAS unsigned char* lds, const Gemm g, const Sched& S, const Epi& E) {
;     ...
; #pragma unroll
;         for (int a = 0; a < 2; ++a)
; #pragma unroll
;             for (int b = 0; b < 2; ++b)
; #pragma unroll
;                 for (int m = 0; m < 4; ++m)
; #pragma unroll
;                     for (int n = 0; n < 2; ++n) acc[a][b][m][n] = (f32x4){0.f, 0.f, 0.f, 0.f};
;         cur = nxt; cA = nA; cB = nB; ++ui;
.LBB0_959:
	s_ashr_i32 s57, s56, 31
	s_lshl_b64 s[58:59], s[56:57], 19
	s_add_u32 s58, s34, s58
	s_addc_u32 s59, s35, s59
	s_and_b64 s[60:61], s[8:9], exec
	s_cselect_b32 s57, s59, s69
	s_cselect_b32 s63, s58, s68
	s_ashr_i32 s55, s54, 31
	s_lshl_b64 s[60:61], s[54:55], 19
	s_add_u32 s60, s33, s60
	s_addc_u32 s61, s73, s61
	s_and_b64 s[64:65], s[8:9], exec
	s_cselect_b32 s55, s61, s67
	s_cselect_b32 s70, s60, s66
	s_lshl_b32 s96, s62, 8
	s_min_i32 s11, s10, 0x100
	s_ashr_i32 s97, s96, 31
	s_lshl_b32 s64, s10, 8
	s_ashr_i32 s12, s11, 3
	s_ashr_i32 s65, s64, 31
	s_lshl_b64 s[10:11], s[96:97], 2
	s_add_u32 s10, s20, s10
	s_addc_u32 s11, s84, s11
	s_mul_hi_i32 s13, s12, 0x3000
	s_mulk_i32 s12, 0x3000
	s_add_u32 s12, s10, s12
	s_addc_u32 s13, s11, s13
	s_lshl_b64 s[10:11], s[64:65], 2
	s_add_u32 s14, s85, s10
	s_addc_u32 s15, s86, s11
	s_and_b64 s[10:11], s[44:45], exec
	s_cselect_b32 s11, s15, s13
	s_cselect_b32 s10, s14, s12
	s_add_u32 s65, s66, 0x100
	s_addc_u32 s71, s67, 0
	v_lshl_add_u64 v[128:129], s[10:11], 0, v[148:149]
	s_add_u32 s10, s68, 0x40080
	v_mov_b64_e32 v[0:1], 0
	v_mov_b64_e32 v[2:3], 0
	v_mov_b64_e32 v[4:5], 0
	v_mov_b64_e32 v[6:7], 0
	v_mov_b64_e32 v[8:9], 0
	v_mov_b64_e32 v[10:11], 0
	v_mov_b64_e32 v[12:13], 0
	v_mov_b64_e32 v[14:15], 0
	v_mov_b64_e32 v[16:17], 0
	v_mov_b64_e32 v[18:19], 0
	v_mov_b64_e32 v[20:21], 0
	v_mov_b64_e32 v[22:23], 0
	v_mov_b64_e32 v[24:25], 0
	v_mov_b64_e32 v[26:27], 0
	v_mov_b64_e32 v[28:29], 0
	v_mov_b64_e32 v[30:31], 0
	v_mov_b64_e32 v[32:33], 0
	v_mov_b64_e32 v[34:35], 0
	v_mov_b64_e32 v[36:37], 0
	v_mov_b64_e32 v[38:39], 0
	v_mov_b64_e32 v[40:41], 0
	v_mov_b64_e32 v[42:43], 0
	v_mov_b64_e32 v[44:45], 0
	v_mov_b64_e32 v[46:47], 0
	v_mov_b64_e32 v[48:49], 0
	v_mov_b64_e32 v[50:51], 0
	v_mov_b64_e32 v[52:53], 0
	v_mov_b64_e32 v[54:55], 0
	v_mov_b64_e32 v[56:57], 0
	v_mov_b64_e32 v[58:59], 0
	v_mov_b64_e32 v[60:61], 0
	v_mov_b64_e32 v[62:63], 0
	v_mov_b64_e32 v[64:65], 0
	v_mov_b64_e32 v[66:67], 0
	v_mov_b64_e32 v[68:69], 0
	v_mov_b64_e32 v[70:71], 0
	v_mov_b64_e32 v[72:73], 0
	v_mov_b64_e32 v[74:75], 0
	v_mov_b64_e32 v[76:77], 0
	v_mov_b64_e32 v[78:79], 0
	v_mov_b64_e32 v[80:81], 0
	v_mov_b64_e32 v[82:83], 0
	v_mov_b64_e32 v[84:85], 0
	v_mov_b64_e32 v[86:87], 0
	v_mov_b64_e32 v[88:89], 0
	v_mov_b64_e32 v[90:91], 0
	v_mov_b64_e32 v[92:93], 0
	v_mov_b64_e32 v[94:95], 0
	v_mov_b64_e32 v[96:97], 0
	v_mov_b64_e32 v[98:99], 0
	v_mov_b64_e32 v[100:101], 0
	v_mov_b64_e32 v[102:103], 0
	v_mov_b64_e32 v[104:105], 0
	v_mov_b64_e32 v[106:107], 0
	v_mov_b64_e32 v[108:109], 0
	v_mov_b64_e32 v[110:111], 0
	v_mov_b64_e32 v[112:113], 0
	v_mov_b64_e32 v[114:115], 0
	v_mov_b64_e32 v[116:117], 0
	v_mov_b64_e32 v[118:119], 0
	v_mov_b64_e32 v[120:121], 0
	v_mov_b64_e32 v[122:123], 0
	v_mov_b64_e32 v[124:125], 0
	v_mov_b64_e32 v[126:127], 0
	s_addc_u32 s11, s69, 0
	s_mov_b32 s96, -2
	s_branch .LBB0_961
	.p2alignl 6, 3212836864

; #define WAIT_BAR(N) asm volatile("s_waitcnt vmcnt(" #N ") lgkmcnt(0)\n\ts_barrier":::"memory")
;   #define DMA_K(t,slot) glds16s(Kb+(long)(t)*KVBLK*kp,ksrc,(unsigned)__builtin_amdgcn_readfirstlane(kdst+(slot)))
;   #define DMA_V(t,slot) do{ glds16s(Vb+(long)(t)*KVBLK*vp,vsrc,(unsigned)__builtin_amdgcn_readfirstlane(vdst+(slot))); \
;       if(VH==2) glds16s(Vb+(long)(t)*KVBLK*vp+64,vsrc,(unsigned)__builtin_amdgcn_readfirstlane(vdst+(slot)+8192)); }while(0)
;   #define BIASADD(P0,P1,t) do{ if(HAS_BIAS&&(t)>=tn0&&(t)<tn1){ const lds_f32*bp_=btab+(64*(t)+lanebias); \
;     _Pragma("unroll") for(int r=0;r<16;++r){ P0[r]+=bp_[(r&3)+8*(r>>2)]; P1[r]+=bp_[(r&3)+8*(r>>2)+32]; } } }while(0)
;   #define ROT() do{sv_prev=sv_cur;sv_cur=sv_next;sv_next=(sv_next==2*VSL)?0:sv_next+VSL;}while(0)
;   #define KPRE(tn) do{ const lds_cptr kn_=kp0+(((tn)&3)*KSL); kf[0]=KLD(kn_); kf[1]=KLD(kn_+512); kf[2]=KLD(kn_+2048); kf[3]=KLD(kn_+2560); }while(0)
; template<int VH,bool HAS_BIAS,int MODE> __device__ __forceinline__ void attn_unit2(const bf16*Qb,int qp,const bf16*__restrict__ Kb,int kp,const bf16*__restrict__ Vb,int vp,bf16*Ob,int op,int q0,int NT,const float*relb,char*shm,float lam,const float*subg,float gmul){
;     ...
;   float l_reg=0.f;f32x16 o[2*VH];
;   #pragma unroll
;   for(int d_=0;d_<2*VH;++d_)o[d_]=f32x16{};
;   const f32x16 zero16=f32x16{};
;   f32x16 pA0,pA1,pB0,pB1; bf16x8 kf[4];
;   int sv_prev=0,sv_cur=0,sv_next=VSL;
;     ...
;   if(VH==1){WAIT_BAR(3);}else{WAIT_BAR(4);}
;   qkt(pA0,pA1,shm+LM::L_K,qr,zero16,r32,hi);
;   BIASADD(pA0,pA1,0);
;   _Pragma("unroll") for(int r=0;r<16;++r){pA0[r]=__builtin_amdgcn_exp2f(pA0[r]);pA1[r]=__builtin_amdgcn_exp2f(pA1[r]);}
;   WAIT_BAR(0);
;   DMA_K(3,3*KSL);DMA_V(1,VSL);
;   ROT();
;   KPRE(1);
.LBB0_1087:
	s_min_i32 s60, s58, s69
	s_add_u32 s42, s44, 0x60000
	s_addc_u32 s43, s45, 0
	s_cmp_lg_u32 0, -1
	s_cselect_b32 s9, 0, 0
	s_add_i32 s7, s9, s7
	s_add_i32 s9, s7, 0x6000
	s_waitcnt vmcnt(0) lgkmcnt(0)
	s_barrier
	s_add_u32 s50, s46, 0x20000
	s_mov_b32 m0, s9
	s_nop 0
	global_load_lds_dwordx4 v202, s[42:43]
	s_addc_u32 s51, s47, 0
	s_add_i32 s9, s7, 0xc000
	s_mov_b32 m0, s9
	s_nop 0
	global_load_lds_dwordx4 v203, s[50:51]
	s_add_u32 s52, s46, 0x20080
	v_mul_f32_e32 v198, 0x3fb8aa3b, v0
	s_addc_u32 s53, s47, 0
	s_add_i32 s7, s7, 0xe000
	s_mov_b32 m0, s7
	s_nop 0
	global_load_lds_dwordx4 v203, s[52:53]
	v_exp_f32_e32 v82, v2
	v_lshlrev_b32_e32 v0, 4, v35
	v_lshlrev_b32_e32 v2, 2, v185
	s_add_i32 s70, s69, -5
	v_sub_u32_e32 v0, v0, v2
	s_lshl_b32 s7, s8, 7
	s_lshl_b32 s78, s54, 10
	s_add_i32 s79, 0, 0x14f00
	s_lshl_b64 s[8:9], s[16:17], 8
	v_lshlrev_b32_e32 v36, 1, v184
	ds_read_b128 v[162:165], v201 offset:10752
	ds_read_b128 v[166:169], v201 offset:10240
	ds_read_b128 v[170:173], v201 offset:8704
	ds_read_b128 v[114:117], v201 offset:8192
	v_subrev_u32_e32 v0, s7, v0
	s_add_u32 s7, s8, s22
	v_and_b32_e32 v197, 32, v36
	v_lshrrev_b32_e32 v36, 2, v184
	s_addc_u32 s8, s9, s23
	v_and_or_b32 v36, v36, 3, v194
	s_add_u32 s71, s30, s7
	v_lshlrev_b32_e32 v196, 6, v36
	v_add_u32_e32 v36, 0, v197
	v_exp_f32_e32 v66, v18
	v_exp_f32_e32 v67, v19
	v_exp_f32_e32 v68, v20
	v_exp_f32_e32 v69, v21
	v_exp_f32_e32 v70, v22
	v_exp_f32_e32 v71, v23
	v_exp_f32_e32 v72, v24
	v_exp_f32_e32 v73, v25
	v_exp_f32_e32 v74, v26
	v_exp_f32_e32 v75, v27
	v_exp_f32_e32 v76, v28
	v_exp_f32_e32 v77, v29
	v_exp_f32_e32 v78, v30
	v_exp_f32_e32 v79, v31
	v_exp_f32_e32 v80, v32
	v_exp_f32_e32 v81, v33
	v_exp_f32_e32 v83, v3
	v_exp_f32_e32 v84, v4
	v_exp_f32_e32 v85, v5
	v_exp_f32_e32 v86, v6
	v_exp_f32_e32 v87, v7
	v_exp_f32_e32 v88, v8
	v_exp_f32_e32 v89, v9
	v_exp_f32_e32 v90, v10
	v_exp_f32_e32 v91, v11
	v_exp_f32_e32 v92, v12
	v_exp_f32_e32 v93, v13
	v_exp_f32_e32 v94, v14
	v_exp_f32_e32 v95, v15
	v_exp_f32_e32 v96, v16
	v_exp_f32_e32 v97, v17
	v_subrev_u32_e32 v0, s78, v0
	s_addc_u32 s73, s31, s8
	s_add_i32 s80, 0, 0x15100
	v_mov_b32_e32 v14, v1
	v_mov_b32_e32 v15, v1
	v_add3_u32 v204, v36, v195, v196
	v_mul_f32_e32 v199, 0x3fb8aa3b, v34
	v_add_u32_e32 v179, s79, v0
	v_add_u32_e32 v205, s80, v0
	v_mov_b32_e32 v0, v1
	v_mov_b32_e32 v2, v1
	v_mov_b32_e32 v3, v1
	v_mov_b32_e32 v4, v1
	v_mov_b32_e32 v5, v1
	v_mov_b32_e32 v6, v1
	v_mov_b32_e32 v7, v1
	v_mov_b32_e32 v8, v1
	v_mov_b32_e32 v9, v1
	v_mov_b32_e32 v10, v1
	v_mov_b32_e32 v11, v1
	v_mov_b32_e32 v12, v1
	v_mov_b32_e32 v13, v1
	v_mov_b64_e32 v[64:65], v[14:15]
	v_mov_b64_e32 v[48:49], v[14:15]
	v_mov_b64_e32 v[32:33], v[14:15]
	v_mov_b64_e32 v[62:63], v[12:13]
	v_mov_b64_e32 v[60:61], v[10:11]
	v_mov_b64_e32 v[58:59], v[8:9]
	v_mov_b64_e32 v[56:57], v[6:7]
	v_mov_b64_e32 v[54:55], v[4:5]
	v_mov_b64_e32 v[52:53], v[2:3]
	v_mov_b64_e32 v[50:51], v[0:1]
	v_mov_b64_e32 v[46:47], v[12:13]
	v_mov_b64_e32 v[44:45], v[10:11]
	v_mov_b64_e32 v[42:43], v[8:9]
	v_mov_b64_e32 v[40:41], v[6:7]
	v_mov_b64_e32 v[38:39], v[4:5]
	v_mov_b64_e32 v[36:37], v[2:3]
	v_mov_b64_e32 v[34:35], v[0:1]
	v_mov_b64_e32 v[30:31], v[12:13]
	v_mov_b64_e32 v[28:29], v[10:11]
	v_mov_b64_e32 v[26:27], v[8:9]
	v_mov_b64_e32 v[24:25], v[6:7]
	v_mov_b64_e32 v[22:23], v[4:5]
	v_mov_b64_e32 v[20:21], v[2:3]
	v_mov_b64_e32 v[18:19], v[0:1]
	v_mov_b64_e32 v[16:17], v[14:15]
	s_mov_b32 s10, 1
	s_mov_b32 s61, 2
	s_mov_b32 s6, 0
	s_mov_b32 s84, 4
	s_sub_i32 s74, 0, s60
	s_sub_i32 s81, 0, s57
	v_mov_b32_e32 v178, 0
	s_movk_i32 s42, 0x4000
	s_mov_b64 s[8:9], 0
	s_mov_b32 s82, 0x8000
	v_mov_b64_e32 v[14:15], v[12:13]
	v_mov_b64_e32 v[12:13], v[10:11]
	v_mov_b64_e32 v[10:11], v[8:9]
	v_mov_b64_e32 v[8:9], v[6:7]
	v_mov_b64_e32 v[6:7], v[4:5]
	v_mov_b64_e32 v[4:5], v[2:3]
	v_mov_b64_e32 v[2:3], v[0:1]
	s_movk_i32 s55, 0x4000
	s_mov_b32 s11, 0x8000
	.p2alignl 6, 3212836864

; #define WAIT_BAR(N) asm volatile("s_waitcnt vmcnt(" #N ") lgkmcnt(0)\n\ts_barrier":::"memory")
;   #define DMA_K(t,slot) glds16s(Kb+(long)(t)*KVBLK*kp,ksrc,(unsigned)__builtin_amdgcn_readfirstlane(kdst+(slot)))
;   #define DMA_V(t,slot) do{ glds16s(Vb+(long)(t)*KVBLK*vp,vsrc,(unsigned)__builtin_amdgcn_readfirstlane(vdst+(slot))); \
;       if(VH==2) glds16s(Vb+(long)(t)*KVBLK*vp+64,vsrc,(unsigned)__builtin_amdgcn_readfirstlane(vdst+(slot)+8192)); }while(0)
;   #define BIASADD(P0,P1,t) do{ if(HAS_BIAS&&(t)>=tn0&&(t)<tn1){ const lds_f32*bp_=btab+(64*(t)+lanebias); \
;     _Pragma("unroll") for(int r=0;r<16;++r){ P0[r]+=bp_[(r&3)+8*(r>>2)]; P1[r]+=bp_[(r&3)+8*(r>>2)+32]; } } }while(0)
;   #define ROT() do{sv_prev=sv_cur;sv_cur=sv_next;sv_next=(sv_next==2*VSL)?0:sv_next+VSL;}while(0)
;   #define KPRE(tn) do{ const lds_cptr kn_=kp0+(((tn)&3)*KSL); kf[0]=KLD(kn_); kf[1]=KLD(kn_+512); kf[2]=KLD(kn_+2048); kf[3]=KLD(kn_+2560); }while(0)
; template<int VH,bool HAS_BIAS,int MODE> __device__ __forceinline__ void attn_unit2(const bf16*Qb,int qp,const bf16*__restrict__ Kb,int kp,const bf16*__restrict__ Vb,int vp,bf16*Ob,int op,int q0,int NT,const float*relb,char*shm,float lam,const float*subg,float gmul){
;     ...
;   float l_reg=0.f;f32x16 o[2*VH];
;   #pragma unroll
;   for(int d_=0;d_<2*VH;++d_)o[d_]=f32x16{};
;   const f32x16 zero16=f32x16{};
;   f32x16 pA0,pA1,pB0,pB1; bf16x8 kf[4];
;   int sv_prev=0,sv_cur=0,sv_next=VSL;
;     ...
;   if(VH==1){WAIT_BAR(3);}else{WAIT_BAR(4);}
;   qkt(pA0,pA1,shm+LM::L_K,qr,zero16,r32,hi);
;   BIASADD(pA0,pA1,0);
;   _Pragma("unroll") for(int r=0;r<16;++r){pA0[r]=__builtin_amdgcn_exp2f(pA0[r]);pA1[r]=__builtin_amdgcn_exp2f(pA1[r]);}
;   WAIT_BAR(0);
;   DMA_K(3,3*KSL);DMA_V(1,VSL);
;   ROT();
;   KPRE(1);
.LBB0_1155:
	s_min_i32 s48, s56, s69
	s_add_u32 s12, s8, 0x60000
	s_addc_u32 s13, s9, 0
	s_cmp_lg_u32 0, -1
	s_cselect_b32 s14, 0, 0
	s_waitcnt vmcnt(0) lgkmcnt(0)
	s_barrier
	s_add_i32 s7, s14, s7
	s_add_i32 s14, s7, 0x6000
	s_mov_b32 m0, s14
	s_nop 0
	global_load_lds_dwordx4 v206, s[12:13]
	s_add_i32 s12, s7, 0xc000
	s_mov_b32 m0, s12
	s_nop 0
	global_load_lds_dwordx4 v207, s[50:51]
	s_add_i32 s7, s7, 0xe000
	s_mov_b32 m0, s7
	s_nop 0
	global_load_lds_dwordx4 v207, s[52:53]
	v_lshlrev_b32_e32 v36, 1, v197
	v_mul_f32_e32 v202, 0x3fb8aa3b, v0
	ds_read_b128 v[162:165], v205 offset:10752
	ds_read_b128 v[166:169], v205 offset:10240
	ds_read_b128 v[170:173], v205 offset:8704
	ds_read_b128 v[114:117], v205 offset:8192
	v_lshlrev_b32_e32 v0, 4, v35
	v_lshlrev_b32_e32 v196, 2, v185
	v_and_b32_e32 v200, 32, v36
	v_bfe_u32 v36, v184, 2, 2
	v_sub_u32_e32 v0, v0, v196
	s_lshl_b32 s7, s54, 7
	v_or_b32_e32 v36, v198, v36
	v_subrev_u32_e32 v0, s7, v0
	v_lshlrev_b32_e32 v201, 6, v36
	v_add_u32_e32 v36, 0, v200
	v_exp_f32_e32 v66, v18
	v_exp_f32_e32 v67, v19
	v_exp_f32_e32 v68, v20
	v_exp_f32_e32 v69, v21
	v_exp_f32_e32 v70, v22
	v_exp_f32_e32 v71, v23
	v_exp_f32_e32 v72, v24
	v_exp_f32_e32 v73, v25
	v_exp_f32_e32 v74, v26
	v_exp_f32_e32 v75, v27
	v_exp_f32_e32 v76, v28
	v_exp_f32_e32 v77, v29
	v_exp_f32_e32 v78, v30
	v_exp_f32_e32 v79, v31
	v_exp_f32_e32 v80, v32
	v_exp_f32_e32 v81, v33
	v_exp_f32_e32 v82, v2
	v_exp_f32_e32 v83, v3
	v_exp_f32_e32 v84, v4
	v_exp_f32_e32 v85, v5
	v_exp_f32_e32 v86, v6
	v_exp_f32_e32 v87, v7
	v_exp_f32_e32 v88, v8
	v_exp_f32_e32 v89, v9
	v_exp_f32_e32 v90, v10
	v_exp_f32_e32 v91, v11
	v_exp_f32_e32 v92, v12
	v_exp_f32_e32 v93, v13
	v_exp_f32_e32 v94, v14
	v_exp_f32_e32 v95, v15
	v_exp_f32_e32 v96, v16
	v_exp_f32_e32 v97, v17
	v_subrev_u32_e32 v0, s78, v0
	v_mov_b32_e32 v14, v1
	v_mov_b32_e32 v15, v1
	v_add3_u32 v208, v36, v199, v201
	v_mul_f32_e32 v203, 0x3fb8aa3b, v34
	v_add_u32_e32 v179, s79, v0
	v_add_u32_e32 v209, s80, v0
	v_mov_b32_e32 v0, v1
	v_mov_b32_e32 v2, v1
	v_mov_b32_e32 v3, v1
	v_mov_b32_e32 v4, v1
	v_mov_b32_e32 v5, v1
	v_mov_b32_e32 v6, v1
	v_mov_b32_e32 v7, v1
	v_mov_b32_e32 v8, v1
	v_mov_b32_e32 v9, v1
	v_mov_b32_e32 v10, v1
	v_mov_b32_e32 v11, v1
	v_mov_b32_e32 v12, v1
	v_mov_b32_e32 v13, v1
	v_mov_b64_e32 v[64:65], v[14:15]
	v_mov_b64_e32 v[48:49], v[14:15]
	v_mov_b64_e32 v[32:33], v[14:15]
	v_mov_b64_e32 v[62:63], v[12:13]
	v_mov_b64_e32 v[60:61], v[10:11]
	v_mov_b64_e32 v[58:59], v[8:9]
	v_mov_b64_e32 v[56:57], v[6:7]
	v_mov_b64_e32 v[54:55], v[4:5]
	v_mov_b64_e32 v[52:53], v[2:3]
	v_mov_b64_e32 v[50:51], v[0:1]
	v_mov_b64_e32 v[46:47], v[12:13]
	v_mov_b64_e32 v[44:45], v[10:11]
	v_mov_b64_e32 v[42:43], v[8:9]
	v_mov_b64_e32 v[40:41], v[6:7]
	v_mov_b64_e32 v[38:39], v[4:5]
	v_mov_b64_e32 v[36:37], v[2:3]
	v_mov_b64_e32 v[34:35], v[0:1]
	v_mov_b64_e32 v[30:31], v[12:13]
	v_mov_b64_e32 v[28:29], v[10:11]
	v_mov_b64_e32 v[26:27], v[8:9]
	v_mov_b64_e32 v[24:25], v[6:7]
	v_mov_b64_e32 v[22:23], v[4:5]
	v_mov_b64_e32 v[20:21], v[2:3]
	v_mov_b64_e32 v[18:19], v[0:1]
	v_mov_b64_e32 v[16:17], v[14:15]
	s_mov_b32 s58, 4
	v_lshrrev_b32_e32 v193, 4, v197
	s_mov_b32 s44, 1
	v_and_b32_e32 v195, 15, v184
	s_mov_b32 s6, 0
	s_mov_b32 s51, 2
	s_sub_i32 s49, 0, s48
	s_sub_i32 s50, 0, s55
	v_mov_b32_e32 v178, 0
	s_movk_i32 s47, 0x4000
	s_mov_b64 s[40:41], 0
	s_mov_b32 s52, 0x8000
	v_mov_b64_e32 v[14:15], v[12:13]
	v_mov_b64_e32 v[12:13], v[10:11]
	v_mov_b64_e32 v[10:11], v[8:9]
	v_mov_b64_e32 v[8:9], v[6:7]
	v_mov_b64_e32 v[6:7], v[4:5]
	v_mov_b64_e32 v[4:5], v[2:3]
	v_mov_b64_e32 v[2:3], v[0:1]
	s_movk_i32 s61, 0x4000
	s_mov_b32 s45, 0x8000
	.p2alignl 6, 3212836864

; template <class Epi, class Sched, bool ALIGN_EPI = false, bool SP2 = false>
; __device__ __forceinline__ void gemm_phase(PG8_LAS unsigned char* lds, const Gemm g, const Sched& S, const Epi& E) {
;     ...
;         const bool has_next = S.next(ui + 1, nxt);
;         const char* nA = has_next ? (const char*)g.A + (size_t)nxt.pm * tstep : cA; const char* nB = has_next ? (const char*)g.Bt + (size_t)nxt.pn * tstep : cB;
;         for (int t = 0; t < nt; t += 2) {
;             const bool last = (t == nt - 2);
;             const char* a1 = cA + (size_t)(t + 1) * kstep;
;             const char* a2 = last ? nA : cA + (size_t)(t + 2) * kstep; const char* b2 = last ? nB : cB + (size_t)(t + 2) * kstep;
;             const char* a3 = a2 + kstep; const char* b3 = b2 + kstep;
;     ...
; #pragma unroll
;         for (int a = 0; a < 2; ++a)
; #pragma unroll
;             for (int b = 0; b < 2; ++b)
; #pragma unroll
;                 for (int m = 0; m < 4; ++m)
; #pragma unroll
;                     for (int n = 0; n < 2; ++n) acc[a][b][m][n] = (f32x4){0.f, 0.f, 0.f, 0.f};
;         cur = nxt; cA = nA; cB = nB; ++ui;
.LBB0_1271:
	s_ashr_i32 s41, s40, 31
	s_lshl_b64 s[42:43], s[40:41], 19
	s_add_u32 s42, s33, s42
	s_addc_u32 s43, s56, s43
	s_and_b64 s[44:45], s[8:9], exec
	s_cselect_b32 s41, s43, s53
	s_cselect_b32 s47, s42, s52
	s_ashr_i32 s39, s38, 31
	s_lshl_b64 s[44:45], s[38:39], 19
	s_add_u32 s44, s57, s44
	s_addc_u32 s45, s58, s45
	s_and_b64 s[54:55], s[8:9], exec
	s_cselect_b32 s39, s45, s51
	s_cselect_b32 s49, s44, s50
	s_add_u32 s77, s50, 0x100
	s_addc_u32 s78, s51, 0
	s_add_u32 s50, s52, 0x40080
	v_mov_b64_e32 v[0:1], 0
	v_mov_b64_e32 v[2:3], 0
	v_mov_b64_e32 v[4:5], 0
	v_mov_b64_e32 v[6:7], 0
	v_mov_b64_e32 v[8:9], 0
	v_mov_b64_e32 v[10:11], 0
	v_mov_b64_e32 v[12:13], 0
	v_mov_b64_e32 v[14:15], 0
	v_mov_b64_e32 v[16:17], 0
	v_mov_b64_e32 v[18:19], 0
	v_mov_b64_e32 v[20:21], 0
	v_mov_b64_e32 v[22:23], 0
	v_mov_b64_e32 v[24:25], 0
	v_mov_b64_e32 v[26:27], 0
	v_mov_b64_e32 v[28:29], 0
	v_mov_b64_e32 v[30:31], 0
	v_mov_b64_e32 v[32:33], 0
	v_mov_b64_e32 v[34:35], 0
	v_mov_b64_e32 v[36:37], 0
	v_mov_b64_e32 v[38:39], 0
	v_mov_b64_e32 v[40:41], 0
	v_mov_b64_e32 v[42:43], 0
	v_mov_b64_e32 v[44:45], 0
	v_mov_b64_e32 v[46:47], 0
	v_mov_b64_e32 v[48:49], 0
	v_mov_b64_e32 v[50:51], 0
	v_mov_b64_e32 v[52:53], 0
	v_mov_b64_e32 v[54:55], 0
	v_mov_b64_e32 v[56:57], 0
	v_mov_b64_e32 v[58:59], 0
	v_mov_b64_e32 v[60:61], 0
	v_mov_b64_e32 v[62:63], 0
	v_mov_b64_e32 v[64:65], 0
	v_mov_b64_e32 v[66:67], 0
	v_mov_b64_e32 v[68:69], 0
	v_mov_b64_e32 v[70:71], 0
	v_mov_b64_e32 v[72:73], 0
	v_mov_b64_e32 v[74:75], 0
	v_mov_b64_e32 v[76:77], 0
	v_mov_b64_e32 v[78:79], 0
	v_mov_b64_e32 v[80:81], 0
	v_mov_b64_e32 v[82:83], 0
	v_mov_b64_e32 v[84:85], 0
	v_mov_b64_e32 v[86:87], 0
	v_mov_b64_e32 v[88:89], 0
	v_mov_b64_e32 v[90:91], 0
	v_mov_b64_e32 v[92:93], 0
	v_mov_b64_e32 v[94:95], 0
	v_mov_b64_e32 v[96:97], 0
	v_mov_b64_e32 v[98:99], 0
	v_mov_b64_e32 v[100:101], 0
	v_mov_b64_e32 v[102:103], 0
	v_mov_b64_e32 v[104:105], 0
	v_mov_b64_e32 v[106:107], 0
	v_mov_b64_e32 v[108:109], 0
	v_mov_b64_e32 v[110:111], 0
	v_mov_b64_e32 v[112:113], 0
	v_mov_b64_e32 v[114:115], 0
	v_mov_b64_e32 v[116:117], 0
	v_mov_b64_e32 v[118:119], 0
	v_mov_b64_e32 v[120:121], 0
	v_mov_b64_e32 v[122:123], 0
	v_mov_b64_e32 v[124:125], 0
	v_mov_b64_e32 v[126:127], 0
	s_addc_u32 s51, s53, 0
	s_mov_b32 s79, -2
	s_waitcnt lgkmcnt(0)
	.p2alignl 6, 3212836864

; #define PG8_LAS __attribute__((address_space(3)))
;     __device__ __forceinline__ void prefetch(PG8_LAS unsigned char* sp, const Unit& u, int wid, int lane) const {
;         const int seq = (u.pm < 256) ? (u.pm >> 3) : 32;
;         const float* src = (wid < 4) ? rowss + u.pm * BM + wid * 64 : bias + (size_t)seq * 5632 + u.pn * HALF + (wid < 6 ? (wid - 4) * 64 : 2816 + (wid - 6) * 64);
;         __builtin_amdgcn_global_load_lds((const unsigned*)(src + lane), (PG8_LAS unsigned*)(sp + wid * 256), 4, 0, 0);
; template <class Epi, class Sched, bool ALIGN_EPI = false, bool SP2 = false>
; __device__ __forceinline__ void gemm_phase(PG8_LAS unsigned char* lds, const Gemm g, const Sched& S, const Epi& E) {
;     ...
; #pragma unroll
;         for (int a = 0; a < 2; ++a)
; #pragma unroll
;             for (int b = 0; b < 2; ++b)
; #pragma unroll
;                 for (int m = 0; m < 4; ++m)
; #pragma unroll
;                     for (int n = 0; n < 2; ++n) acc[a][b][m][n] = (f32x4){0.f, 0.f, 0.f, 0.f};
;         cur = nxt; cA = nA; cB = nB; ++ui;
.LBB0_1357:
	s_ashr_i32 s39, s38, 31
	s_lshl_b64 s[40:41], s[38:39], 19
	s_add_u32 s40, s34, s40
	s_addc_u32 s41, s35, s41
	s_and_b64 s[42:43], s[6:7], exec
	s_cselect_b32 s39, s41, s53
	s_cselect_b32 s73, s40, s52
	s_ashr_i32 s37, s36, 31
	s_lshl_b64 s[42:43], s[36:37], 19
	s_add_u32 s42, s33, s42
	s_addc_u32 s43, s54, s43
	s_and_b64 s[46:47], s[6:7], exec
	s_cselect_b32 s37, s43, s49
	s_cselect_b32 s74, s42, s48
	s_lshl_b32 s44, s44, 7
	s_lshl_b32 s46, s50, 8
	s_ashr_i32 s14, s50, 3
	s_ashr_i32 s45, s44, 31
	s_ashr_i32 s47, s46, 31
	s_cmpk_lt_i32 s50, 0x100
	s_mul_i32 s15, s14, 0x1600
	s_mul_hi_i32 s14, s14, 0x1600
	s_cselect_b32 s51, s14, 0
	s_cselect_b32 s50, s15, 0x2c000
	s_lshl_b64 s[50:51], s[50:51], 2
	s_add_u32 s14, s62, s50
	s_addc_u32 s15, s63, s51
	s_lshl_b64 s[50:51], s[44:45], 2
	s_add_u32 s14, s14, s50
	s_addc_u32 s15, s15, s51
	s_add_u32 s14, s14, s16
	s_addc_u32 s15, s15, s17
	s_lshl_b64 s[50:51], s[46:47], 2
	s_add_u32 s45, s68, s50
	s_addc_u32 s47, s69, s51
	s_and_b64 s[50:51], s[20:21], exec
	s_cselect_b32 s51, s47, s15
	s_cselect_b32 s50, s45, s14
	s_add_u32 s45, s48, 0x100
	s_addc_u32 s47, s49, 0
	s_add_u32 s48, s52, 0x40080
	v_mov_b64_e32 v[0:1], 0
	v_mov_b64_e32 v[2:3], 0
	v_mov_b64_e32 v[4:5], 0
	v_mov_b64_e32 v[6:7], 0
	v_mov_b64_e32 v[8:9], 0
	v_mov_b64_e32 v[10:11], 0
	v_mov_b64_e32 v[12:13], 0
	v_mov_b64_e32 v[14:15], 0
	v_mov_b64_e32 v[16:17], 0
	v_mov_b64_e32 v[18:19], 0
	v_mov_b64_e32 v[20:21], 0
	v_mov_b64_e32 v[22:23], 0
	v_mov_b64_e32 v[24:25], 0
	v_mov_b64_e32 v[26:27], 0
	v_mov_b64_e32 v[28:29], 0
	v_mov_b64_e32 v[30:31], 0
	v_mov_b64_e32 v[32:33], 0
	v_mov_b64_e32 v[34:35], 0
	v_mov_b64_e32 v[36:37], 0
	v_mov_b64_e32 v[38:39], 0
	v_mov_b64_e32 v[40:41], 0
	v_mov_b64_e32 v[42:43], 0
	v_mov_b64_e32 v[44:45], 0
	v_mov_b64_e32 v[46:47], 0
	v_mov_b64_e32 v[48:49], 0
	v_mov_b64_e32 v[50:51], 0
	v_mov_b64_e32 v[52:53], 0
	v_mov_b64_e32 v[54:55], 0
	v_mov_b64_e32 v[56:57], 0
	v_mov_b64_e32 v[58:59], 0
	v_mov_b64_e32 v[60:61], 0
	v_mov_b64_e32 v[62:63], 0
	v_mov_b64_e32 v[64:65], 0
	v_mov_b64_e32 v[66:67], 0
	v_mov_b64_e32 v[68:69], 0
	v_mov_b64_e32 v[70:71], 0
	v_mov_b64_e32 v[72:73], 0
	v_mov_b64_e32 v[74:75], 0
	v_mov_b64_e32 v[76:77], 0
	v_mov_b64_e32 v[78:79], 0
	v_mov_b64_e32 v[80:81], 0
	v_mov_b64_e32 v[82:83], 0
	v_mov_b64_e32 v[84:85], 0
	v_mov_b64_e32 v[86:87], 0
	v_mov_b64_e32 v[88:89], 0
	v_mov_b64_e32 v[90:91], 0
	v_mov_b64_e32 v[92:93], 0
	v_mov_b64_e32 v[94:95], 0
	v_mov_b64_e32 v[96:97], 0
	v_mov_b64_e32 v[98:99], 0
	v_mov_b64_e32 v[100:101], 0
	v_mov_b64_e32 v[102:103], 0
	v_mov_b64_e32 v[104:105], 0
	v_mov_b64_e32 v[106:107], 0
	v_mov_b64_e32 v[108:109], 0
	v_mov_b64_e32 v[110:111], 0
	v_mov_b64_e32 v[112:113], 0
	v_mov_b64_e32 v[114:115], 0
	v_mov_b64_e32 v[132:133], 0
	v_mov_b64_e32 v[134:135], 0
	v_mov_b64_e32 v[136:137], 0
	v_mov_b64_e32 v[138:139], 0
	v_mov_b64_e32 v[140:141], 0
	v_mov_b64_e32 v[142:143], 0
	v_lshl_add_u64 v[116:117], s[50:51], 0, v[160:161]
	s_addc_u32 s49, s53, 0
	s_mov_b32 s75, -2
	s_branch .LBB0_1359
	.p2alignl 6, 3212836864

; template <class Epi, class Sched, bool ALIGN_EPI = false, bool SP2 = false>
; __device__ __forceinline__ void gemm_phase(PG8_LAS unsigned char* lds, const Gemm g, const Sched& S, const Epi& E) {
;     ...
;             const char* a1 = cA + (size_t)(t + 1) * kstep;
;             const char* a2 = last ? nA : cA + (size_t)(t + 2) * kstep; const char* b2 = last ? nB : cB + (size_t)(t + 2) * kstep;
;     ...
; #pragma unroll
;         for (int a = 0; a < 2; ++a)
; #pragma unroll
;             for (int b = 0; b < 2; ++b)
; #pragma unroll
;                 for (int m = 0; m < 4; ++m)
; #pragma unroll
;                     for (int n = 0; n < 2; ++n) acc[a][b][m][n] = (f32x4){0.f, 0.f, 0.f, 0.f};
;         cur = nxt; cA = nA; cB = nB; ++ui;
.LBB0_1431:
	s_add_u32 s50, s20, 0x100
	v_mov_b64_e32 v[0:1], 0
	v_mov_b64_e32 v[2:3], 0
	v_mov_b64_e32 v[4:5], 0
	v_mov_b64_e32 v[6:7], 0
	v_mov_b64_e32 v[8:9], 0
	v_mov_b64_e32 v[10:11], 0
	v_mov_b64_e32 v[12:13], 0
	v_mov_b64_e32 v[14:15], 0
	v_mov_b64_e32 v[16:17], 0
	v_mov_b64_e32 v[18:19], 0
	v_mov_b64_e32 v[20:21], 0
	v_mov_b64_e32 v[22:23], 0
	v_mov_b64_e32 v[24:25], 0
	v_mov_b64_e32 v[26:27], 0
	v_mov_b64_e32 v[28:29], 0
	v_mov_b64_e32 v[30:31], 0
	v_mov_b64_e32 v[32:33], 0
	v_mov_b64_e32 v[34:35], 0
	v_mov_b64_e32 v[36:37], 0
	v_mov_b64_e32 v[38:39], 0
	v_mov_b64_e32 v[40:41], 0
	v_mov_b64_e32 v[42:43], 0
	v_mov_b64_e32 v[44:45], 0
	v_mov_b64_e32 v[46:47], 0
	v_mov_b64_e32 v[48:49], 0
	v_mov_b64_e32 v[50:51], 0
	v_mov_b64_e32 v[52:53], 0
	v_mov_b64_e32 v[54:55], 0
	v_mov_b64_e32 v[56:57], 0
	v_mov_b64_e32 v[58:59], 0
	v_mov_b64_e32 v[60:61], 0
	v_mov_b64_e32 v[62:63], 0
	v_mov_b64_e32 v[64:65], 0
	v_mov_b64_e32 v[66:67], 0
	v_mov_b64_e32 v[68:69], 0
	v_mov_b64_e32 v[70:71], 0
	v_mov_b64_e32 v[72:73], 0
	v_mov_b64_e32 v[74:75], 0
	v_mov_b64_e32 v[76:77], 0
	v_mov_b64_e32 v[78:79], 0
	v_mov_b64_e32 v[80:81], 0
	v_mov_b64_e32 v[82:83], 0
	v_mov_b64_e32 v[84:85], 0
	v_mov_b64_e32 v[86:87], 0
	v_mov_b64_e32 v[88:89], 0
	v_mov_b64_e32 v[90:91], 0
	v_mov_b64_e32 v[92:93], 0
	v_mov_b64_e32 v[94:95], 0
	v_mov_b64_e32 v[96:97], 0
	v_mov_b64_e32 v[98:99], 0
	v_mov_b64_e32 v[100:101], 0
	v_mov_b64_e32 v[102:103], 0
	v_mov_b64_e32 v[104:105], 0
	v_mov_b64_e32 v[106:107], 0
	v_mov_b64_e32 v[108:109], 0
	v_mov_b64_e32 v[110:111], 0
	v_mov_b64_e32 v[112:113], 0
	v_mov_b64_e32 v[114:115], 0
	v_mov_b64_e32 v[116:117], 0
	v_mov_b64_e32 v[118:119], 0
	v_mov_b64_e32 v[120:121], 0
	v_mov_b64_e32 v[122:123], 0
	v_mov_b64_e32 v[124:125], 0
	v_mov_b64_e32 v[126:127], 0
	s_addc_u32 s51, s21, 0
	s_mov_b32 s52, -2
	.p2alignl 6, 3212836864
